# v39 plus nt hint on the one-shot f32 weight reads of the conversion phase (read once, should not displace the converted weights / activations from the memory-side cache)
# baseline (speedup 1.0000x reference)
; __device__ __forceinline__ void conv_matrix(const float* W, int K, int N, int Nv, bf16_t* WT, int mode, LAS float* scr, int gw, int ngw, int lane, const float* nscale = nullptr) {
;     ...
;     for (int it = gw; it < nitems; it += ngw) {
;         const int kb = it / nblk, nb = it % nblk, k0 = 64 * kb, n0 = 64 * nb;
;         const bool ok = (n0 + c4) < N;
;         const float* src = W + (size_t)(k0 + r4) * N + n0 + c4;
;         f32x4 v[16];
; #pragma unroll
;         for (int i = 0; i < 16; ++i) v[i] = ok ? *(const f32x4*)(src + (size_t)(4 * i) * N) : (f32x4){0.f, 0.f, 0.f, 0.f};
.LBB0_15:
	s_mul_hi_i32 s4, s35, 0x51eb851f
	s_lshr_b32 s5, s4, 31
	s_ashr_i32 s4, s4, 5
	s_add_i32 s4, s4, s5
	s_lshl_b32 s16, s4, 6
	s_mulk_i32 s4, 0xe700
	s_add_i32 s18, s34, s4
	v_add_u32_e32 v2, s18, v70
	s_movk_i32 s4, 0x1810
	v_cmp_gt_i32_e64 s[4:5], s4, v2
	v_or_b32_e32 v2, s16, v71
	v_mad_i64_i32 v[2:3], s[20:21], v2, s23, v[76:77]
	s_ashr_i32 s19, s18, 31
	v_lshl_add_u64 v[2:3], s[18:19], 2, v[2:3]
	v_lshl_add_u64 v[78:79], v[2:3], 0, v[68:69]
	v_mov_b32_e32 v6, 0
	v_mov_b32_e32 v2, 0
	v_mov_b32_e32 v3, 0
	v_mov_b32_e32 v4, 0
	v_mov_b32_e32 v5, 0
	s_and_saveexec_b64 s[20:21], s[4:5]
	s_cbranch_execz .LBB0_17
	global_load_dwordx4 v[2:5], v[78:79], off nt
.LBB0_17:
	s_or_b64 exec, exec, s[20:21]
	v_mov_b32_e32 v7, 0
	v_mov_b32_e32 v8, 0
	v_mov_b32_e32 v9, 0
	s_and_saveexec_b64 s[20:21], s[4:5]
	s_cbranch_execz .LBB0_19
	v_add_co_u32_e32 v6, vcc, 0x18000, v78
	s_nop 1
	v_addc_co_u32_e32 v7, vcc, 0, v79, vcc
	global_load_dwordx4 v[6:9], v[6:7], off offset:256 nt
.LBB0_19:
	s_or_b64 exec, exec, s[20:21]
	v_mov_b32_e32 v10, 0
	v_mov_b32_e32 v14, 0
	v_mov_b32_e32 v15, 0
	v_mov_b32_e32 v16, 0
	v_mov_b32_e32 v17, 0
	s_and_saveexec_b64 s[20:21], s[4:5]
	s_cbranch_execz .LBB0_21
	v_add_co_u32_e32 v12, vcc, 0x30000, v78
	s_nop 1
	v_addc_co_u32_e32 v13, vcc, 0, v79, vcc
	global_load_dwordx4 v[14:17], v[12:13], off offset:512 nt
.LBB0_21:
	s_or_b64 exec, exec, s[20:21]
	v_mov_b32_e32 v11, 0
	v_mov_b32_e32 v12, 0
	v_mov_b32_e32 v13, 0
	s_and_saveexec_b64 s[20:21], s[4:5]
	s_cbranch_execz .LBB0_23
	v_add_co_u32_e32 v10, vcc, 0x48000, v78
	s_nop 1
	v_addc_co_u32_e32 v11, vcc, 0, v79, vcc
	global_load_dwordx4 v[10:13], v[10:11], off offset:768 nt
.LBB0_23:
	s_or_b64 exec, exec, s[20:21]
	v_mov_b32_e32 v18, 0
	v_mov_b32_e32 v22, 0
	v_mov_b32_e32 v23, 0
	v_mov_b32_e32 v24, 0
	v_mov_b32_e32 v25, 0
	s_and_saveexec_b64 s[20:21], s[4:5]
	s_cbranch_execz .LBB0_25
	v_add_co_u32_e32 v20, vcc, 0x60000, v78
	s_nop 1
	v_addc_co_u32_e32 v21, vcc, 0, v79, vcc
	global_load_dwordx4 v[22:25], v[20:21], off offset:1024 nt
.LBB0_25:
	s_or_b64 exec, exec, s[20:21]
	v_mov_b32_e32 v19, 0
	v_mov_b32_e32 v20, 0
	v_mov_b32_e32 v21, 0
	s_and_saveexec_b64 s[20:21], s[4:5]
	s_cbranch_execz .LBB0_27
	v_add_co_u32_e32 v18, vcc, 0x78000, v78
	s_nop 1
	v_addc_co_u32_e32 v19, vcc, 0, v79, vcc
	global_load_dwordx4 v[18:21], v[18:19], off offset:1280 nt
.LBB0_27:
	s_or_b64 exec, exec, s[20:21]
	v_mov_b32_e32 v26, 0
	v_mov_b32_e32 v30, 0
	v_mov_b32_e32 v31, 0
	v_mov_b32_e32 v32, 0
	v_mov_b32_e32 v33, 0
	s_and_saveexec_b64 s[20:21], s[4:5]
	s_cbranch_execz .LBB0_29
	v_add_co_u32_e32 v28, vcc, 0x90000, v78
	s_nop 1
	v_addc_co_u32_e32 v29, vcc, 0, v79, vcc
	global_load_dwordx4 v[30:33], v[28:29], off offset:1536 nt
.LBB0_29:
	s_or_b64 exec, exec, s[20:21]
	v_mov_b32_e32 v27, 0
	v_mov_b32_e32 v28, 0
	v_mov_b32_e32 v29, 0
	s_and_saveexec_b64 s[20:21], s[4:5]
	s_cbranch_execz .LBB0_31
	v_add_co_u32_e32 v26, vcc, 0xa8000, v78
	s_nop 1
	v_addc_co_u32_e32 v27, vcc, 0, v79, vcc
	global_load_dwordx4 v[26:29], v[26:27], off offset:1792 nt
.LBB0_31:
	s_or_b64 exec, exec, s[20:21]
	v_mov_b32_e32 v34, 0
	v_mov_b32_e32 v38, 0
	v_mov_b32_e32 v39, 0
	v_mov_b32_e32 v40, 0
	v_mov_b32_e32 v41, 0
	s_and_saveexec_b64 s[20:21], s[4:5]
	s_cbranch_execz .LBB0_33
	v_add_co_u32_e32 v36, vcc, 0xc0000, v78
	s_nop 1
	v_addc_co_u32_e32 v37, vcc, 0, v79, vcc
	global_load_dwordx4 v[38:41], v[36:37], off offset:2048 nt
.LBB0_33:
	s_or_b64 exec, exec, s[20:21]
	v_mov_b32_e32 v35, 0
	v_mov_b32_e32 v36, 0
	v_mov_b32_e32 v37, 0
	s_and_saveexec_b64 s[20:21], s[4:5]
	s_cbranch_execz .LBB0_35
	v_add_co_u32_e32 v34, vcc, 0xd8000, v78
	s_nop 1
	v_addc_co_u32_e32 v35, vcc, 0, v79, vcc
	global_load_dwordx4 v[34:37], v[34:35], off offset:2304 nt
.LBB0_35:
	s_or_b64 exec, exec, s[20:21]
	v_mov_b32_e32 v42, 0
	v_mov_b32_e32 v46, 0
	v_mov_b32_e32 v47, 0
	v_mov_b32_e32 v48, 0
	v_mov_b32_e32 v49, 0
	s_and_saveexec_b64 s[20:21], s[4:5]
	s_cbranch_execz .LBB0_37
	v_add_co_u32_e32 v44, vcc, 0xf0000, v78
	s_nop 1
	v_addc_co_u32_e32 v45, vcc, 0, v79, vcc
	global_load_dwordx4 v[46:49], v[44:45], off offset:2560 nt
.LBB0_37:
	s_or_b64 exec, exec, s[20:21]
	v_mov_b32_e32 v43, 0
	v_mov_b32_e32 v44, 0
	v_mov_b32_e32 v45, 0
	s_and_saveexec_b64 s[20:21], s[4:5]
	s_cbranch_execz .LBB0_39
	v_add_co_u32_e32 v42, vcc, 0x108000, v78
	s_nop 1
	v_addc_co_u32_e32 v43, vcc, 0, v79, vcc
	global_load_dwordx4 v[42:45], v[42:43], off offset:2816 nt
.LBB0_39:
	s_or_b64 exec, exec, s[20:21]
	v_mov_b32_e32 v50, 0
	v_mov_b32_e32 v54, 0
	v_mov_b32_e32 v55, 0
	v_mov_b32_e32 v56, 0
	v_mov_b32_e32 v57, 0
	s_and_saveexec_b64 s[20:21], s[4:5]
	s_cbranch_execz .LBB0_41
	v_add_co_u32_e32 v52, vcc, 0x120000, v78
	s_nop 1
	v_addc_co_u32_e32 v53, vcc, 0, v79, vcc
	global_load_dwordx4 v[54:57], v[52:53], off offset:3072 nt
.LBB0_41:
	s_or_b64 exec, exec, s[20:21]
	v_mov_b32_e32 v51, 0
	v_mov_b32_e32 v52, 0
	v_mov_b32_e32 v53, 0
	s_and_saveexec_b64 s[20:21], s[4:5]
	s_cbranch_execz .LBB0_43
	v_add_co_u32_e32 v50, vcc, 0x138000, v78
	s_nop 1
	v_addc_co_u32_e32 v51, vcc, 0, v79, vcc
	global_load_dwordx4 v[50:53], v[50:51], off offset:3328 nt
.LBB0_43:
	s_or_b64 exec, exec, s[20:21]
	v_mov_b32_e32 v58, 0
	v_mov_b32_e32 v62, 0
	v_mov_b32_e32 v63, 0
	v_mov_b32_e32 v64, 0
	v_mov_b32_e32 v65, 0
	s_and_saveexec_b64 s[20:21], s[4:5]
	s_cbranch_execz .LBB0_45
	v_add_co_u32_e32 v60, vcc, 0x150000, v78
	s_nop 1
	v_addc_co_u32_e32 v61, vcc, 0, v79, vcc
	global_load_dwordx4 v[62:65], v[60:61], off offset:3584 nt
.LBB0_45:
	s_or_b64 exec, exec, s[20:21]
	v_mov_b32_e32 v59, 0
	v_mov_b32_e32 v60, 0
	v_mov_b32_e32 v61, 0
	s_and_saveexec_b64 s[20:21], s[4:5]
	s_cbranch_execz .LBB0_14
	v_add_co_u32_e32 v58, vcc, 0x168000, v78
	s_nop 1
	v_addc_co_u32_e32 v59, vcc, 0, v79, vcc
	global_load_dwordx4 v[58:61], v[58:59], off offset:3840 nt
	s_branch .LBB0_14

; __device__ __forceinline__ void conv_matrix(const float* W, int K, int N, int Nv, bf16_t* WT, int mode, LAS float* scr, int gw, int ngw, int lane, const float* nscale = nullptr) {
;     ...
;     for (int it = gw; it < nitems; it += ngw) {
;         const int kb = it / nblk, nb = it % nblk, k0 = 64 * kb, n0 = 64 * nb;
;         const bool ok = (n0 + c4) < N;
;         const float* src = W + (size_t)(k0 + r4) * N + n0 + c4;
;         f32x4 v[16];
; #pragma unroll
;         for (int i = 0; i < 16; ++i) v[i] = ok ? *(const f32x4*)(src + (size_t)(4 * i) * N) : (f32x4){0.f, 0.f, 0.f, 0.f};
.LBB0_51:
	s_ashr_i32 s8, s35, 31
	s_lshr_b32 s8, s8, 27
	s_add_i32 s8, s35, s8
	s_ashr_i32 s8, s8, 5
	s_lshl_b32 s19, s8, 11
	s_sub_i32 s20, s34, s19
	s_lshl_b32 s18, s8, 6
	v_add_u32_e32 v2, s20, v70
	v_cmp_gt_i32_e64 s[8:9], s33, v2
	v_or_b32_e32 v2, s18, v71
	v_ashrrev_i32_e32 v3, 31, v2
	v_lshlrev_b64 v[2:3], 13, v[2:3]
	v_lshl_add_u64 v[2:3], s[14:15], 0, v[2:3]
	s_ashr_i32 s21, s20, 31
	v_lshl_add_u64 v[2:3], s[20:21], 2, v[2:3]
	v_mov_b32_e32 v73, v67
	v_lshl_add_u64 v[76:77], v[2:3], 0, v[72:73]
	v_mov_b32_e32 v6, 0
	v_mov_b32_e32 v2, 0
	v_mov_b32_e32 v3, 0
	v_mov_b32_e32 v4, 0
	v_mov_b32_e32 v5, 0
	s_and_saveexec_b64 s[20:21], s[8:9]
	s_cbranch_execz .LBB0_53
	global_load_dwordx4 v[2:5], v[76:77], off nt
.LBB0_53:
	s_or_b64 exec, exec, s[20:21]
	v_mov_b32_e32 v7, 0
	v_mov_b32_e32 v8, 0
	v_mov_b32_e32 v9, 0
	s_and_saveexec_b64 s[20:21], s[8:9]
	s_cbranch_execz .LBB0_55
	v_add_co_u32_e32 v6, vcc, 0x8000, v76
	s_nop 1
	v_addc_co_u32_e32 v7, vcc, 0, v77, vcc
	global_load_dwordx4 v[6:9], v[6:7], off nt
.LBB0_55:
	s_or_b64 exec, exec, s[20:21]
	v_mov_b32_e32 v10, 0
	v_mov_b32_e32 v14, 0
	v_mov_b32_e32 v15, 0
	v_mov_b32_e32 v16, 0
	v_mov_b32_e32 v17, 0
	s_and_saveexec_b64 s[20:21], s[8:9]
	s_cbranch_execz .LBB0_57
	v_add_co_u32_e32 v12, vcc, 0x10000, v76
	s_nop 1
	v_addc_co_u32_e32 v13, vcc, 0, v77, vcc
	global_load_dwordx4 v[14:17], v[12:13], off nt
.LBB0_57:
	s_or_b64 exec, exec, s[20:21]
	v_mov_b32_e32 v11, 0
	v_mov_b32_e32 v12, 0
	v_mov_b32_e32 v13, 0
	s_and_saveexec_b64 s[20:21], s[8:9]
	s_cbranch_execz .LBB0_59
	v_add_co_u32_e32 v10, vcc, 0x18000, v76
	s_nop 1
	v_addc_co_u32_e32 v11, vcc, 0, v77, vcc
	global_load_dwordx4 v[10:13], v[10:11], off nt
.LBB0_59:
	s_or_b64 exec, exec, s[20:21]
	v_mov_b32_e32 v18, 0
	v_mov_b32_e32 v22, 0
	v_mov_b32_e32 v23, 0
	v_mov_b32_e32 v24, 0
	v_mov_b32_e32 v25, 0
	s_and_saveexec_b64 s[20:21], s[8:9]
	s_cbranch_execz .LBB0_61
	v_add_co_u32_e32 v20, vcc, 0x20000, v76
	s_nop 1
	v_addc_co_u32_e32 v21, vcc, 0, v77, vcc
	global_load_dwordx4 v[22:25], v[20:21], off nt
.LBB0_61:
	s_or_b64 exec, exec, s[20:21]
	v_mov_b32_e32 v19, 0
	v_mov_b32_e32 v20, 0
	v_mov_b32_e32 v21, 0
	s_and_saveexec_b64 s[20:21], s[8:9]
	s_cbranch_execz .LBB0_63
	v_add_co_u32_e32 v18, vcc, 0x28000, v76
	s_nop 1
	v_addc_co_u32_e32 v19, vcc, 0, v77, vcc
	global_load_dwordx4 v[18:21], v[18:19], off nt
.LBB0_63:
	s_or_b64 exec, exec, s[20:21]
	v_mov_b32_e32 v26, 0
	v_mov_b32_e32 v30, 0
	v_mov_b32_e32 v31, 0
	v_mov_b32_e32 v32, 0
	v_mov_b32_e32 v33, 0
	s_and_saveexec_b64 s[20:21], s[8:9]
	s_cbranch_execz .LBB0_65
	v_add_co_u32_e32 v28, vcc, 0x30000, v76
	s_nop 1
	v_addc_co_u32_e32 v29, vcc, 0, v77, vcc
	global_load_dwordx4 v[30:33], v[28:29], off nt
.LBB0_65:
	s_or_b64 exec, exec, s[20:21]
	v_mov_b32_e32 v27, 0
	v_mov_b32_e32 v28, 0
	v_mov_b32_e32 v29, 0
	s_and_saveexec_b64 s[20:21], s[8:9]
	s_cbranch_execz .LBB0_67
	v_add_co_u32_e32 v26, vcc, 0x38000, v76
	s_nop 1
	v_addc_co_u32_e32 v27, vcc, 0, v77, vcc
	global_load_dwordx4 v[26:29], v[26:27], off nt
.LBB0_67:
	s_or_b64 exec, exec, s[20:21]
	v_mov_b32_e32 v34, 0
	v_mov_b32_e32 v38, 0
	v_mov_b32_e32 v39, 0
	v_mov_b32_e32 v40, 0
	v_mov_b32_e32 v41, 0
	s_and_saveexec_b64 s[20:21], s[8:9]
	s_cbranch_execz .LBB0_69
	v_add_co_u32_e32 v36, vcc, 0x40000, v76
	s_nop 1
	v_addc_co_u32_e32 v37, vcc, 0, v77, vcc
	global_load_dwordx4 v[38:41], v[36:37], off nt
.LBB0_69:
	s_or_b64 exec, exec, s[20:21]
	v_mov_b32_e32 v35, 0
	v_mov_b32_e32 v36, 0
	v_mov_b32_e32 v37, 0
	s_and_saveexec_b64 s[20:21], s[8:9]
	s_cbranch_execz .LBB0_71
	v_add_co_u32_e32 v34, vcc, 0x48000, v76
	s_nop 1
	v_addc_co_u32_e32 v35, vcc, 0, v77, vcc
	global_load_dwordx4 v[34:37], v[34:35], off nt
.LBB0_71:
	s_or_b64 exec, exec, s[20:21]
	v_mov_b32_e32 v42, 0
	v_mov_b32_e32 v46, 0
	v_mov_b32_e32 v47, 0
	v_mov_b32_e32 v48, 0
	v_mov_b32_e32 v49, 0
	s_and_saveexec_b64 s[20:21], s[8:9]
	s_cbranch_execz .LBB0_73
	v_add_co_u32_e32 v44, vcc, 0x50000, v76
	s_nop 1
	v_addc_co_u32_e32 v45, vcc, 0, v77, vcc
	global_load_dwordx4 v[46:49], v[44:45], off nt
.LBB0_73:
	s_or_b64 exec, exec, s[20:21]
	v_mov_b32_e32 v43, 0
	v_mov_b32_e32 v44, 0
	v_mov_b32_e32 v45, 0
	s_and_saveexec_b64 s[20:21], s[8:9]
	s_cbranch_execz .LBB0_75
	v_add_co_u32_e32 v42, vcc, 0x58000, v76
	s_nop 1
	v_addc_co_u32_e32 v43, vcc, 0, v77, vcc
	global_load_dwordx4 v[42:45], v[42:43], off nt
.LBB0_75:
	s_or_b64 exec, exec, s[20:21]
	v_mov_b32_e32 v50, 0
	v_mov_b32_e32 v54, 0
	v_mov_b32_e32 v55, 0
	v_mov_b32_e32 v56, 0
	v_mov_b32_e32 v57, 0
	s_and_saveexec_b64 s[20:21], s[8:9]
	s_cbranch_execz .LBB0_77
	v_add_co_u32_e32 v52, vcc, 0x60000, v76
	s_nop 1
	v_addc_co_u32_e32 v53, vcc, 0, v77, vcc
	global_load_dwordx4 v[54:57], v[52:53], off nt
.LBB0_77:
	s_or_b64 exec, exec, s[20:21]
	v_mov_b32_e32 v51, 0
	v_mov_b32_e32 v52, 0
	v_mov_b32_e32 v53, 0
	s_and_saveexec_b64 s[20:21], s[8:9]
	s_cbranch_execz .LBB0_79
	v_add_co_u32_e32 v50, vcc, 0x68000, v76
	s_nop 1
	v_addc_co_u32_e32 v51, vcc, 0, v77, vcc
	global_load_dwordx4 v[50:53], v[50:51], off nt
.LBB0_79:
	s_or_b64 exec, exec, s[20:21]
	v_mov_b32_e32 v58, 0
	v_mov_b32_e32 v62, 0
	v_mov_b32_e32 v63, 0
	v_mov_b32_e32 v64, 0
	v_mov_b32_e32 v65, 0
	s_and_saveexec_b64 s[20:21], s[8:9]
	s_cbranch_execz .LBB0_81
	v_add_co_u32_e32 v60, vcc, 0x70000, v76
	s_nop 1
	v_addc_co_u32_e32 v61, vcc, 0, v77, vcc
	global_load_dwordx4 v[62:65], v[60:61], off nt
.LBB0_81:
	s_or_b64 exec, exec, s[20:21]
	s_sub_i32 s19, 0, s19
	v_mov_b32_e32 v59, 0
	v_mov_b32_e32 v60, 0
	v_mov_b32_e32 v61, 0
	s_and_saveexec_b64 s[20:21], s[8:9]
	s_cbranch_execz .LBB0_50
	v_add_co_u32_e32 v58, vcc, 0x78000, v76
	s_nop 1
	v_addc_co_u32_e32 v59, vcc, 0, v77, vcc
	global_load_dwordx4 v[58:61], v[58:59], off nt
	s_branch .LBB0_50

; __device__ __forceinline__ void conv_matrix(const float* W, int K, int N, int Nv, bf16_t* WT, int mode, LAS float* scr, int gw, int ngw, int lane, const float* nscale = nullptr) {
;     ...
;     for (int it = gw; it < nitems; it += ngw) {
;         const int kb = it / nblk, nb = it % nblk, k0 = 64 * kb, n0 = 64 * nb;
;         const bool ok = (n0 + c4) < N;
;         const float* src = W + (size_t)(k0 + r4) * N + n0 + c4;
;         f32x4 v[16];
; #pragma unroll
;         for (int i = 0; i < 16; ++i) v[i] = ok ? *(const f32x4*)(src + (size_t)(4 * i) * N) : (f32x4){0.f, 0.f, 0.f, 0.f};
.LBB0_89:
	s_ashr_i32 s8, s36, 31
	s_lshr_b32 s8, s8, 29
	s_add_i32 s8, s36, s8
	s_ashr_i32 s8, s8, 3
	s_lshl_b32 s18, s8, 6
	v_or_b32_e32 v4, s18, v71
	s_lshl_b32 s19, s8, 9
	v_ashrrev_i32_e32 v5, 31, v4
	s_sub_i32 s20, s12, s19
	v_lshlrev_b64 v[4:5], 11, v[4:5]
	v_lshl_add_u64 v[4:5], s[14:15], 0, v[4:5]
	s_ashr_i32 s21, s20, 31
	v_lshl_add_u64 v[4:5], s[20:21], 2, v[4:5]
	v_add_u32_e32 v3, s20, v70
	v_lshl_add_u64 v[80:81], v[4:5], 0, v[72:73]
	v_mov_b32_e32 v4, v2
	v_mov_b32_e32 v5, v2
	v_cmp_gt_i32_e64 s[8:9], s27, v3
	v_mov_b32_e32 v3, v2
	v_mov_b64_e32 v[8:9], v[4:5]
	v_mov_b64_e32 v[6:7], v[2:3]
	s_and_saveexec_b64 s[22:23], s[8:9]
	s_cbranch_execz .LBB0_91
	global_load_dwordx4 v[6:9], v[80:81], off nt
.LBB0_91:
	s_or_b64 exec, exec, s[22:23]
	v_mov_b64_e32 v[12:13], v[4:5]
	v_mov_b64_e32 v[10:11], v[2:3]
	s_and_saveexec_b64 s[22:23], s[8:9]
	s_cbranch_execz .LBB0_93
	v_add_co_u32_e32 v4, vcc, 0x2000, v80
	s_nop 1
	v_addc_co_u32_e32 v5, vcc, 0, v81, vcc
	global_load_dwordx4 v[10:13], v[4:5], off nt
.LBB0_93:
	s_or_b64 exec, exec, s[22:23]
	v_mov_b32_e32 v4, v2
	v_mov_b32_e32 v5, v2
	v_mov_b32_e32 v3, v2
	v_mov_b64_e32 v[16:17], v[4:5]
	v_mov_b64_e32 v[14:15], v[2:3]
	s_and_saveexec_b64 s[22:23], s[8:9]
	s_cbranch_execz .LBB0_95
	v_add_co_u32_e32 v14, vcc, 0x4000, v80
	s_nop 1
	v_addc_co_u32_e32 v15, vcc, 0, v81, vcc
	global_load_dwordx4 v[14:17], v[14:15], off nt
.LBB0_95:
	s_or_b64 exec, exec, s[22:23]
	v_mov_b64_e32 v[20:21], v[4:5]
	v_mov_b64_e32 v[18:19], v[2:3]
	s_and_saveexec_b64 s[22:23], s[8:9]
	s_cbranch_execz .LBB0_97
	v_add_co_u32_e32 v4, vcc, 0x6000, v80
	s_nop 1
	v_addc_co_u32_e32 v5, vcc, 0, v81, vcc
	global_load_dwordx4 v[18:21], v[4:5], off nt
.LBB0_97:
	s_or_b64 exec, exec, s[22:23]
	v_mov_b32_e32 v4, v2
	v_mov_b32_e32 v5, v2
	v_mov_b32_e32 v3, v2
	v_mov_b64_e32 v[24:25], v[4:5]
	v_mov_b64_e32 v[22:23], v[2:3]
	s_and_saveexec_b64 s[22:23], s[8:9]
	s_cbranch_execz .LBB0_99
	v_add_co_u32_e32 v22, vcc, 0x8000, v80
	s_nop 1
	v_addc_co_u32_e32 v23, vcc, 0, v81, vcc
	global_load_dwordx4 v[22:25], v[22:23], off nt
.LBB0_99:
	s_or_b64 exec, exec, s[22:23]
	v_mov_b64_e32 v[28:29], v[4:5]
	v_mov_b64_e32 v[26:27], v[2:3]
	s_and_saveexec_b64 s[22:23], s[8:9]
	s_cbranch_execz .LBB0_101
	v_add_co_u32_e32 v4, vcc, 0xa000, v80
	s_nop 1
	v_addc_co_u32_e32 v5, vcc, 0, v81, vcc
	global_load_dwordx4 v[26:29], v[4:5], off nt
.LBB0_101:
	s_or_b64 exec, exec, s[22:23]
	v_mov_b32_e32 v4, v2
	v_mov_b32_e32 v5, v2
	v_mov_b32_e32 v3, v2
	v_mov_b64_e32 v[32:33], v[4:5]
	v_mov_b64_e32 v[30:31], v[2:3]
	s_and_saveexec_b64 s[22:23], s[8:9]
	s_cbranch_execz .LBB0_103
	v_add_co_u32_e32 v30, vcc, 0xc000, v80
	s_nop 1
	v_addc_co_u32_e32 v31, vcc, 0, v81, vcc
	global_load_dwordx4 v[30:33], v[30:31], off nt
.LBB0_103:
	s_or_b64 exec, exec, s[22:23]
	v_mov_b64_e32 v[36:37], v[4:5]
	v_mov_b64_e32 v[34:35], v[2:3]
	s_and_saveexec_b64 s[22:23], s[8:9]
	s_cbranch_execz .LBB0_105
	v_add_co_u32_e32 v4, vcc, 0xe000, v80
	s_nop 1
	v_addc_co_u32_e32 v5, vcc, 0, v81, vcc
	global_load_dwordx4 v[34:37], v[4:5], off nt
.LBB0_105:
	s_or_b64 exec, exec, s[22:23]
	v_mov_b32_e32 v4, v2
	v_mov_b32_e32 v5, v2
	v_mov_b32_e32 v3, v2
	v_mov_b64_e32 v[40:41], v[4:5]
	v_mov_b64_e32 v[38:39], v[2:3]
	s_and_saveexec_b64 s[22:23], s[8:9]
	s_cbranch_execz .LBB0_107
	v_add_co_u32_e32 v38, vcc, 0x10000, v80
	s_nop 1
	v_addc_co_u32_e32 v39, vcc, 0, v81, vcc
	global_load_dwordx4 v[38:41], v[38:39], off nt
.LBB0_107:
	s_or_b64 exec, exec, s[22:23]
	v_mov_b64_e32 v[44:45], v[4:5]
	v_mov_b64_e32 v[42:43], v[2:3]
	s_and_saveexec_b64 s[22:23], s[8:9]
	s_cbranch_execz .LBB0_109
	v_add_co_u32_e32 v4, vcc, 0x12000, v80
	s_nop 1
	v_addc_co_u32_e32 v5, vcc, 0, v81, vcc
	global_load_dwordx4 v[42:45], v[4:5], off nt
; __device__ __forceinline__ void conv_matrix(const float* W, int K, int N, int Nv, bf16_t* WT, int mode, LAS float* scr, int gw, int ngw, int lane, const float* nscale = nullptr) {
;     ...
;         for (int i = 0; i < 16; ++i) v[i] = ok ? *(const f32x4*)(src + (size_t)(4 * i) * N) : (f32x4){0.f, 0.f, 0.f, 0.f};
;         if (nscale) { const f32x4 s4 = *(const f32x4*)(nscale + n0 + c4);
; #pragma unroll
;             for (int i = 0; i < 16; ++i) v[i] = v[i] * s4; }
.LBB0_109:
	s_or_b64 exec, exec, s[22:23]
	v_mov_b32_e32 v4, v2
	v_mov_b32_e32 v5, v2
	v_mov_b32_e32 v3, v2
	v_mov_b64_e32 v[48:49], v[4:5]
	v_mov_b64_e32 v[46:47], v[2:3]
	s_and_saveexec_b64 s[22:23], s[8:9]
	s_cbranch_execz .LBB0_111
	v_add_co_u32_e32 v46, vcc, 0x14000, v80
	s_nop 1
	v_addc_co_u32_e32 v47, vcc, 0, v81, vcc
	global_load_dwordx4 v[46:49], v[46:47], off nt
.LBB0_111:
	s_or_b64 exec, exec, s[22:23]
	v_mov_b64_e32 v[52:53], v[4:5]
	v_mov_b64_e32 v[50:51], v[2:3]
	s_and_saveexec_b64 s[22:23], s[8:9]
	s_cbranch_execz .LBB0_113
	v_add_co_u32_e32 v4, vcc, 0x16000, v80
	s_nop 1
	v_addc_co_u32_e32 v5, vcc, 0, v81, vcc
	global_load_dwordx4 v[50:53], v[4:5], off nt
.LBB0_113:
	s_or_b64 exec, exec, s[22:23]
	v_mov_b32_e32 v4, v2
	v_mov_b32_e32 v5, v2
	v_mov_b32_e32 v3, v2
	v_mov_b64_e32 v[56:57], v[4:5]
	v_mov_b64_e32 v[54:55], v[2:3]
	s_and_saveexec_b64 s[22:23], s[8:9]
	s_cbranch_execz .LBB0_115
	v_add_co_u32_e32 v54, vcc, 0x18000, v80
	s_nop 1
	v_addc_co_u32_e32 v55, vcc, 0, v81, vcc
	global_load_dwordx4 v[54:57], v[54:55], off nt
.LBB0_115:
	s_or_b64 exec, exec, s[22:23]
	v_mov_b64_e32 v[60:61], v[4:5]
	v_mov_b64_e32 v[58:59], v[2:3]
	s_and_saveexec_b64 s[22:23], s[8:9]
	s_cbranch_execz .LBB0_117
	v_add_co_u32_e32 v4, vcc, 0x1a000, v80
	s_nop 1
	v_addc_co_u32_e32 v5, vcc, 0, v81, vcc
	global_load_dwordx4 v[58:61], v[4:5], off nt
.LBB0_117:
	s_or_b64 exec, exec, s[22:23]
	v_mov_b32_e32 v4, v2
	v_mov_b32_e32 v5, v2
	v_mov_b32_e32 v3, v2
	v_mov_b64_e32 v[64:65], v[4:5]
	v_mov_b64_e32 v[62:63], v[2:3]
	s_and_saveexec_b64 s[22:23], s[8:9]
	s_cbranch_execz .LBB0_119
	v_add_co_u32_e32 v62, vcc, 0x1c000, v80
	s_nop 1
	v_addc_co_u32_e32 v63, vcc, 0, v81, vcc
	global_load_dwordx4 v[62:65], v[62:63], off nt
.LBB0_119:
	s_or_b64 exec, exec, s[22:23]
	v_mov_b64_e32 v[68:69], v[4:5]
	v_mov_b64_e32 v[66:67], v[2:3]
	s_and_saveexec_b64 s[22:23], s[8:9]
	s_cbranch_execz .LBB0_121
	v_add_co_u32_e32 v4, vcc, 0x1e000, v80
	s_nop 1
	v_addc_co_u32_e32 v5, vcc, 0, v81, vcc
	global_load_dwordx4 v[66:69], v[4:5], off nt
.LBB0_121:
	s_or_b64 exec, exec, s[22:23]
	s_andn2_b64 vcc, exec, s[0:1]
	s_sub_i32 s8, 0, s19
	s_cbranch_vccnz .LBB0_88
	v_lshl_add_u64 v[4:5], s[20:21], 2, v[78:79]
	global_load_dwordx4 v[86:89], v[4:5], off nt
	s_waitcnt vmcnt(0)
	v_pk_mul_f32 v[8:9], v[8:9], v[88:89]
	v_pk_mul_f32 v[6:7], v[6:7], v[86:87]
	v_pk_mul_f32 v[12:13], v[12:13], v[88:89]
	v_pk_mul_f32 v[10:11], v[10:11], v[86:87]
	v_pk_mul_f32 v[16:17], v[16:17], v[88:89]
	v_pk_mul_f32 v[14:15], v[14:15], v[86:87]
	v_pk_mul_f32 v[20:21], v[20:21], v[88:89]
	v_pk_mul_f32 v[18:19], v[18:19], v[86:87]
	v_pk_mul_f32 v[24:25], v[24:25], v[88:89]
	v_pk_mul_f32 v[22:23], v[22:23], v[86:87]
	v_pk_mul_f32 v[28:29], v[28:29], v[88:89]
	v_pk_mul_f32 v[26:27], v[26:27], v[86:87]
	v_pk_mul_f32 v[32:33], v[32:33], v[88:89]
	v_pk_mul_f32 v[30:31], v[30:31], v[86:87]
	v_pk_mul_f32 v[36:37], v[36:37], v[88:89]
	v_pk_mul_f32 v[34:35], v[34:35], v[86:87]
	v_pk_mul_f32 v[40:41], v[40:41], v[88:89]
	v_pk_mul_f32 v[38:39], v[38:39], v[86:87]
	v_pk_mul_f32 v[44:45], v[44:45], v[88:89]
	v_pk_mul_f32 v[42:43], v[42:43], v[86:87]
	v_pk_mul_f32 v[48:49], v[48:49], v[88:89]
	v_pk_mul_f32 v[46:47], v[46:47], v[86:87]
	v_pk_mul_f32 v[52:53], v[52:53], v[88:89]
	v_pk_mul_f32 v[50:51], v[50:51], v[86:87]
	v_pk_mul_f32 v[56:57], v[56:57], v[88:89]
	v_pk_mul_f32 v[54:55], v[54:55], v[86:87]
	v_pk_mul_f32 v[60:61], v[60:61], v[88:89]
	v_pk_mul_f32 v[58:59], v[58:59], v[86:87]
	v_pk_mul_f32 v[64:65], v[64:65], v[88:89]
	v_pk_mul_f32 v[62:63], v[62:63], v[86:87]
	v_pk_mul_f32 v[68:69], v[68:69], v[88:89]
	v_pk_mul_f32 v[66:67], v[66:67], v[86:87]
	s_branch .LBB0_88

; __device__ __forceinline__ void conv_matrix(const float* W, int K, int N, int Nv, bf16_t* WT, int mode, LAS float* scr, int gw, int ngw, int lane, const float* nscale = nullptr) {
;     ...
;     for (int it = gw; it < nitems; it += ngw) {
;         const int kb = it / nblk, nb = it % nblk, k0 = 64 * kb, n0 = 64 * nb;
;         const bool ok = (n0 + c4) < N;
;         const float* src = W + (size_t)(k0 + r4) * N + n0 + c4;
;         f32x4 v[16];
; #pragma unroll
;         for (int i = 0; i < 16; ++i) v[i] = ok ? *(const f32x4*)(src + (size_t)(4 * i) * N) : (f32x4){0.f, 0.f, 0.f, 0.f};
.LBB0_126:
	s_mul_hi_i32 s0, s23, 0x2aaaaaab
	s_lshr_b32 s1, s0, 31
	s_ashr_i32 s0, s0, 4
	s_add_i32 s1, s0, s1
	s_lshl_b32 s0, s1, 6
	s_mulk_i32 s1, 0xe800
	s_add_i32 s8, s14, s1
	v_add_u32_e32 v2, s8, v70
	v_cmp_gt_i32_e64 s[6:7], s15, v2
	v_or_b32_e32 v2, s0, v71
	v_mad_i64_i32 v[2:3], s[12:13], v2, s16, v[68:69]
	s_ashr_i32 s9, s8, 31
	v_lshl_add_u64 v[2:3], s[8:9], 2, v[2:3]
	v_lshl_add_u64 v[74:75], v[2:3], 0, v[72:73]
	v_mov_b32_e32 v2, 0
	v_mov_b32_e32 v3, 0
	v_mov_b32_e32 v4, 0
	v_mov_b32_e32 v5, 0
	s_and_saveexec_b64 s[12:13], s[6:7]
	s_cbranch_execz .LBB0_128
	global_load_dwordx4 v[2:5], v[74:75], off nt
.LBB0_128:
	s_or_b64 exec, exec, s[12:13]
	v_mov_b32_e32 v6, 0
	v_mov_b32_e32 v10, 0
	v_mov_b32_e32 v11, 0
	v_mov_b32_e32 v12, 0
	v_mov_b32_e32 v13, 0
	s_and_saveexec_b64 s[12:13], s[6:7]
	s_cbranch_execz .LBB0_130
	v_add_co_u32_e32 v8, vcc, 0x18000, v74
	s_nop 1
	v_addc_co_u32_e32 v9, vcc, 0, v75, vcc
	global_load_dwordx4 v[10:13], v[8:9], off nt
.LBB0_130:
	s_or_b64 exec, exec, s[12:13]
	v_mov_b32_e32 v7, 0
	v_mov_b32_e32 v8, 0
	v_mov_b32_e32 v9, 0
	s_and_saveexec_b64 s[12:13], s[6:7]
	s_cbranch_execz .LBB0_132
	v_add_co_u32_e32 v6, vcc, 0x30000, v74
	s_nop 1
	v_addc_co_u32_e32 v7, vcc, 0, v75, vcc
	global_load_dwordx4 v[6:9], v[6:7], off nt
.LBB0_132:
	s_or_b64 exec, exec, s[12:13]
	v_mov_b32_e32 v14, 0
	v_mov_b32_e32 v18, 0
	v_mov_b32_e32 v19, 0
	v_mov_b32_e32 v20, 0
	v_mov_b32_e32 v21, 0
	s_and_saveexec_b64 s[12:13], s[6:7]
	s_cbranch_execz .LBB0_134
	v_add_co_u32_e32 v16, vcc, 0x48000, v74
	s_nop 1
	v_addc_co_u32_e32 v17, vcc, 0, v75, vcc
	global_load_dwordx4 v[18:21], v[16:17], off nt
.LBB0_134:
	s_or_b64 exec, exec, s[12:13]
	v_mov_b32_e32 v15, 0
	v_mov_b32_e32 v16, 0
	v_mov_b32_e32 v17, 0
	s_and_saveexec_b64 s[12:13], s[6:7]
	s_cbranch_execz .LBB0_136
	v_add_co_u32_e32 v14, vcc, 0x60000, v74
	s_nop 1
	v_addc_co_u32_e32 v15, vcc, 0, v75, vcc
	global_load_dwordx4 v[14:17], v[14:15], off nt
.LBB0_136:
	s_or_b64 exec, exec, s[12:13]
	v_mov_b32_e32 v22, 0
	v_mov_b32_e32 v26, 0
	v_mov_b32_e32 v27, 0
	v_mov_b32_e32 v28, 0
	v_mov_b32_e32 v29, 0
	s_and_saveexec_b64 s[12:13], s[6:7]
	s_cbranch_execz .LBB0_138
	v_add_co_u32_e32 v24, vcc, 0x78000, v74
	s_nop 1
	v_addc_co_u32_e32 v25, vcc, 0, v75, vcc
	global_load_dwordx4 v[26:29], v[24:25], off nt
.LBB0_138:
	s_or_b64 exec, exec, s[12:13]
	v_mov_b32_e32 v23, 0
	v_mov_b32_e32 v24, 0
	v_mov_b32_e32 v25, 0
	s_and_saveexec_b64 s[12:13], s[6:7]
	s_cbranch_execz .LBB0_140
	v_add_co_u32_e32 v22, vcc, 0x90000, v74
	s_nop 1
	v_addc_co_u32_e32 v23, vcc, 0, v75, vcc
	global_load_dwordx4 v[22:25], v[22:23], off nt
.LBB0_140:
	s_or_b64 exec, exec, s[12:13]
	v_mov_b32_e32 v30, 0
	v_mov_b32_e32 v34, 0
	v_mov_b32_e32 v35, 0
	v_mov_b32_e32 v36, 0
	v_mov_b32_e32 v37, 0
	s_and_saveexec_b64 s[12:13], s[6:7]
	s_cbranch_execz .LBB0_142
	v_add_co_u32_e32 v32, vcc, 0xa8000, v74
	s_nop 1
	v_addc_co_u32_e32 v33, vcc, 0, v75, vcc
	global_load_dwordx4 v[34:37], v[32:33], off nt
.LBB0_142:
	s_or_b64 exec, exec, s[12:13]
	v_mov_b32_e32 v31, 0
	v_mov_b32_e32 v32, 0
	v_mov_b32_e32 v33, 0
	s_and_saveexec_b64 s[12:13], s[6:7]
	s_cbranch_execz .LBB0_144
	v_add_co_u32_e32 v30, vcc, 0xc0000, v74
	s_nop 1
	v_addc_co_u32_e32 v31, vcc, 0, v75, vcc
	global_load_dwordx4 v[30:33], v[30:31], off nt
.LBB0_144:
	s_or_b64 exec, exec, s[12:13]
	v_mov_b32_e32 v38, 0
	v_mov_b32_e32 v42, 0
	v_mov_b32_e32 v43, 0
	v_mov_b32_e32 v44, 0
	v_mov_b32_e32 v45, 0
	s_and_saveexec_b64 s[12:13], s[6:7]
	s_cbranch_execz .LBB0_146
	v_add_co_u32_e32 v40, vcc, 0xd8000, v74
	s_nop 1
	v_addc_co_u32_e32 v41, vcc, 0, v75, vcc
	global_load_dwordx4 v[42:45], v[40:41], off nt
.LBB0_146:
	s_or_b64 exec, exec, s[12:13]
	v_mov_b32_e32 v39, 0
	v_mov_b32_e32 v40, 0
	v_mov_b32_e32 v41, 0
	s_and_saveexec_b64 s[12:13], s[6:7]
	s_cbranch_execz .LBB0_148
	v_add_co_u32_e32 v38, vcc, 0xf0000, v74
	s_nop 1
	v_addc_co_u32_e32 v39, vcc, 0, v75, vcc
	global_load_dwordx4 v[38:41], v[38:39], off nt
.LBB0_148:
	s_or_b64 exec, exec, s[12:13]
	v_mov_b32_e32 v46, 0
	v_mov_b32_e32 v50, 0
	v_mov_b32_e32 v51, 0
	v_mov_b32_e32 v52, 0
	v_mov_b32_e32 v53, 0
	s_and_saveexec_b64 s[12:13], s[6:7]
	s_cbranch_execz .LBB0_150
	v_add_co_u32_e32 v48, vcc, 0x108000, v74
	s_nop 1
	v_addc_co_u32_e32 v49, vcc, 0, v75, vcc
	global_load_dwordx4 v[50:53], v[48:49], off nt
.LBB0_150:
	s_or_b64 exec, exec, s[12:13]
	v_mov_b32_e32 v47, 0
	v_mov_b32_e32 v48, 0
	v_mov_b32_e32 v49, 0
	s_and_saveexec_b64 s[12:13], s[6:7]
	s_cbranch_execz .LBB0_152
	v_add_co_u32_e32 v46, vcc, 0x120000, v74
	s_nop 1
	v_addc_co_u32_e32 v47, vcc, 0, v75, vcc
	global_load_dwordx4 v[46:49], v[46:47], off nt
.LBB0_152:
	s_or_b64 exec, exec, s[12:13]
	v_mov_b32_e32 v54, 0
	v_mov_b32_e32 v58, 0
	v_mov_b32_e32 v59, 0
	v_mov_b32_e32 v60, 0
	v_mov_b32_e32 v61, 0
	s_and_saveexec_b64 s[12:13], s[6:7]
	s_cbranch_execz .LBB0_154
	v_add_co_u32_e32 v56, vcc, 0x138000, v74
	s_nop 1
	v_addc_co_u32_e32 v57, vcc, 0, v75, vcc
	global_load_dwordx4 v[58:61], v[56:57], off nt
.LBB0_154:
	s_or_b64 exec, exec, s[12:13]
	v_mov_b32_e32 v55, 0
	v_mov_b32_e32 v56, 0
	v_mov_b32_e32 v57, 0
	s_and_saveexec_b64 s[12:13], s[6:7]
	s_cbranch_execz .LBB0_156
	v_add_co_u32_e32 v54, vcc, 0x150000, v74
	s_nop 1
	v_addc_co_u32_e32 v55, vcc, 0, v75, vcc
	global_load_dwordx4 v[54:57], v[54:55], off nt
.LBB0_156:
	s_or_b64 exec, exec, s[12:13]
	v_mov_b32_e32 v62, 0
	v_mov_b32_e32 v63, 0
	v_mov_b32_e32 v64, 0
	v_mov_b32_e32 v65, 0
	s_and_saveexec_b64 s[12:13], s[6:7]
	s_cbranch_execz .LBB0_125
	v_add_co_u32_e32 v62, vcc, 0x168000, v74
	s_nop 1
	v_addc_co_u32_e32 v63, vcc, 0, v75, vcc
	global_load_dwordx4 v[62:65], v[62:63], off nt
	s_branch .LBB0_125

; __device__ __forceinline__ void conv_matrix(const float* W, int K, int N, int Nv, bf16_t* WT, int mode, LAS float* scr, int gw, int ngw, int lane, const float* nscale = nullptr) {
;     ...
;     for (int it = gw; it < nitems; it += ngw) {
;         const int kb = it / nblk, nb = it % nblk, k0 = 64 * kb, n0 = 64 * nb;
;         const bool ok = (n0 + c4) < N;
;         const float* src = W + (size_t)(k0 + r4) * N + n0 + c4;
;         f32x4 v[16];
; #pragma unroll
;         for (int i = 0; i < 16; ++i) v[i] = ok ? *(const f32x4*)(src + (size_t)(4 * i) * N) : (f32x4){0.f, 0.f, 0.f, 0.f};
.LBB0_161:
	s_ashr_i32 s0, s18, 31
	s_lshr_b32 s0, s0, 27
	s_add_i32 s0, s18, s0
	s_ashr_i32 s1, s0, 5
	s_lshl_b32 s0, s1, 6
	s_lshl_b32 s1, s1, 11
	s_sub_i32 s6, s8, s1
	v_add_u32_e32 v2, s6, v70
	v_cmp_gt_i32_e64 s[4:5], s9, v2
	v_or_b32_e32 v2, s0, v71
	v_ashrrev_i32_e32 v3, 31, v2
	v_lshlrev_b64 v[2:3], 13, v[2:3]
	v_lshl_add_u64 v[2:3], s[64:65], 0, v[2:3]
	s_ashr_i32 s7, s6, 31
	v_lshl_add_u64 v[2:3], s[6:7], 2, v[2:3]
	v_lshl_add_u64 v[68:69], v[2:3], 0, v[72:73]
	v_mov_b32_e32 v2, 0
	v_mov_b32_e32 v3, 0
	v_mov_b32_e32 v4, 0
	v_mov_b32_e32 v5, 0
	s_and_saveexec_b64 s[6:7], s[4:5]
	s_cbranch_execz .LBB0_163
	global_load_dwordx4 v[2:5], v[68:69], off nt
.LBB0_163:
	s_or_b64 exec, exec, s[6:7]
	v_mov_b32_e32 v6, 0
	v_mov_b32_e32 v10, 0
	v_mov_b32_e32 v11, 0
	v_mov_b32_e32 v12, 0
	v_mov_b32_e32 v13, 0
	s_and_saveexec_b64 s[6:7], s[4:5]
	s_cbranch_execz .LBB0_165
	v_add_co_u32_e32 v8, vcc, 0x8000, v68
	s_nop 1
	v_addc_co_u32_e32 v9, vcc, 0, v69, vcc
	global_load_dwordx4 v[10:13], v[8:9], off nt
.LBB0_165:
	s_or_b64 exec, exec, s[6:7]
	v_mov_b32_e32 v7, 0
	v_mov_b32_e32 v8, 0
	v_mov_b32_e32 v9, 0
	s_and_saveexec_b64 s[6:7], s[4:5]
	s_cbranch_execz .LBB0_167
	v_add_co_u32_e32 v6, vcc, 0x10000, v68
	s_nop 1
	v_addc_co_u32_e32 v7, vcc, 0, v69, vcc
	global_load_dwordx4 v[6:9], v[6:7], off nt
.LBB0_167:
	s_or_b64 exec, exec, s[6:7]
	v_mov_b32_e32 v14, 0
	v_mov_b32_e32 v18, 0
	v_mov_b32_e32 v19, 0
	v_mov_b32_e32 v20, 0
	v_mov_b32_e32 v21, 0
	s_and_saveexec_b64 s[6:7], s[4:5]
	s_cbranch_execz .LBB0_169
	v_add_co_u32_e32 v16, vcc, 0x18000, v68
	s_nop 1
	v_addc_co_u32_e32 v17, vcc, 0, v69, vcc
	global_load_dwordx4 v[18:21], v[16:17], off nt
.LBB0_169:
	s_or_b64 exec, exec, s[6:7]
	v_mov_b32_e32 v15, 0
	v_mov_b32_e32 v16, 0
	v_mov_b32_e32 v17, 0
	s_and_saveexec_b64 s[6:7], s[4:5]
	s_cbranch_execz .LBB0_171
	v_add_co_u32_e32 v14, vcc, 0x20000, v68
	s_nop 1
	v_addc_co_u32_e32 v15, vcc, 0, v69, vcc
	global_load_dwordx4 v[14:17], v[14:15], off nt
.LBB0_171:
	s_or_b64 exec, exec, s[6:7]
	v_mov_b32_e32 v22, 0
	v_mov_b32_e32 v26, 0
	v_mov_b32_e32 v27, 0
	v_mov_b32_e32 v28, 0
	v_mov_b32_e32 v29, 0
	s_and_saveexec_b64 s[6:7], s[4:5]
	s_cbranch_execz .LBB0_173
	v_add_co_u32_e32 v24, vcc, 0x28000, v68
	s_nop 1
	v_addc_co_u32_e32 v25, vcc, 0, v69, vcc
	global_load_dwordx4 v[26:29], v[24:25], off nt
.LBB0_173:
	s_or_b64 exec, exec, s[6:7]
	v_mov_b32_e32 v23, 0
	v_mov_b32_e32 v24, 0
	v_mov_b32_e32 v25, 0
	s_and_saveexec_b64 s[6:7], s[4:5]
	s_cbranch_execz .LBB0_175
	v_add_co_u32_e32 v22, vcc, 0x30000, v68
	s_nop 1
	v_addc_co_u32_e32 v23, vcc, 0, v69, vcc
	global_load_dwordx4 v[22:25], v[22:23], off nt
.LBB0_175:
	s_or_b64 exec, exec, s[6:7]
	v_mov_b32_e32 v30, 0
	v_mov_b32_e32 v34, 0
	v_mov_b32_e32 v35, 0
	v_mov_b32_e32 v36, 0
	v_mov_b32_e32 v37, 0
	s_and_saveexec_b64 s[6:7], s[4:5]
	s_cbranch_execz .LBB0_177
	v_add_co_u32_e32 v32, vcc, 0x38000, v68
	s_nop 1
	v_addc_co_u32_e32 v33, vcc, 0, v69, vcc
	global_load_dwordx4 v[34:37], v[32:33], off nt
.LBB0_177:
	s_or_b64 exec, exec, s[6:7]
	v_mov_b32_e32 v31, 0
	v_mov_b32_e32 v32, 0
	v_mov_b32_e32 v33, 0
	s_and_saveexec_b64 s[6:7], s[4:5]
	s_cbranch_execz .LBB0_179
	v_add_co_u32_e32 v30, vcc, 0x40000, v68
	s_nop 1
	v_addc_co_u32_e32 v31, vcc, 0, v69, vcc
	global_load_dwordx4 v[30:33], v[30:31], off nt
.LBB0_179:
	s_or_b64 exec, exec, s[6:7]
	v_mov_b32_e32 v38, 0
	v_mov_b32_e32 v42, 0
	v_mov_b32_e32 v43, 0
	v_mov_b32_e32 v44, 0
	v_mov_b32_e32 v45, 0
	s_and_saveexec_b64 s[6:7], s[4:5]
	s_cbranch_execz .LBB0_181
	v_add_co_u32_e32 v40, vcc, 0x48000, v68
	s_nop 1
	v_addc_co_u32_e32 v41, vcc, 0, v69, vcc
	global_load_dwordx4 v[42:45], v[40:41], off nt
.LBB0_181:
	s_or_b64 exec, exec, s[6:7]
	v_mov_b32_e32 v39, 0
	v_mov_b32_e32 v40, 0
	v_mov_b32_e32 v41, 0
	s_and_saveexec_b64 s[6:7], s[4:5]
	s_cbranch_execz .LBB0_183
	v_add_co_u32_e32 v38, vcc, 0x50000, v68
	s_nop 1
	v_addc_co_u32_e32 v39, vcc, 0, v69, vcc
	global_load_dwordx4 v[38:41], v[38:39], off nt
.LBB0_183:
	s_or_b64 exec, exec, s[6:7]
	v_mov_b32_e32 v46, 0
	v_mov_b32_e32 v50, 0
	v_mov_b32_e32 v51, 0
	v_mov_b32_e32 v52, 0
	v_mov_b32_e32 v53, 0
	s_and_saveexec_b64 s[6:7], s[4:5]
	s_cbranch_execz .LBB0_185
	v_add_co_u32_e32 v48, vcc, 0x58000, v68
	s_nop 1
	v_addc_co_u32_e32 v49, vcc, 0, v69, vcc
	global_load_dwordx4 v[50:53], v[48:49], off nt
.LBB0_185:
	s_or_b64 exec, exec, s[6:7]
	v_mov_b32_e32 v47, 0
	v_mov_b32_e32 v48, 0
	v_mov_b32_e32 v49, 0
	s_and_saveexec_b64 s[6:7], s[4:5]
	s_cbranch_execz .LBB0_187
	v_add_co_u32_e32 v46, vcc, 0x60000, v68
	s_nop 1
	v_addc_co_u32_e32 v47, vcc, 0, v69, vcc
	global_load_dwordx4 v[46:49], v[46:47], off nt
.LBB0_187:
	s_or_b64 exec, exec, s[6:7]
	v_mov_b32_e32 v54, 0
	v_mov_b32_e32 v58, 0
	v_mov_b32_e32 v59, 0
	v_mov_b32_e32 v60, 0
	v_mov_b32_e32 v61, 0
	s_and_saveexec_b64 s[6:7], s[4:5]
	s_cbranch_execz .LBB0_189
	v_add_co_u32_e32 v56, vcc, 0x68000, v68
	s_nop 1
	v_addc_co_u32_e32 v57, vcc, 0, v69, vcc
	global_load_dwordx4 v[58:61], v[56:57], off nt
.LBB0_189:
	s_or_b64 exec, exec, s[6:7]
	v_mov_b32_e32 v55, 0
	v_mov_b32_e32 v56, 0
	v_mov_b32_e32 v57, 0
	s_and_saveexec_b64 s[6:7], s[4:5]
	s_cbranch_execz .LBB0_191
	v_add_co_u32_e32 v54, vcc, 0x70000, v68
	s_nop 1
	v_addc_co_u32_e32 v55, vcc, 0, v69, vcc
	global_load_dwordx4 v[54:57], v[54:55], off nt
.LBB0_191:
	s_or_b64 exec, exec, s[6:7]
	s_sub_i32 s1, 0, s1
	v_mov_b32_e32 v62, 0
	v_mov_b32_e32 v63, 0
	v_mov_b32_e32 v64, 0
	v_mov_b32_e32 v65, 0
	s_and_saveexec_b64 s[6:7], s[4:5]
	s_cbranch_execz .LBB0_160
	v_add_co_u32_e32 v62, vcc, 0x78000, v68
	s_nop 1
	v_addc_co_u32_e32 v63, vcc, 0, v69, vcc
	global_load_dwordx4 v[62:65], v[62:63], off nt
	s_branch .LBB0_160

; __device__ __forceinline__ void conv_matrix(const float* W, int K, int N, int Nv, bf16_t* WT, int mode, LAS float* scr, int gw, int ngw, int lane, const float* nscale = nullptr) {
;     ...
;     for (int it = gw; it < nitems; it += ngw) {
;         const int kb = it / nblk, nb = it % nblk, k0 = 64 * kb, n0 = 64 * nb;
;         const bool ok = (n0 + c4) < N;
;         const float* src = W + (size_t)(k0 + r4) * N + n0 + c4;
;         f32x4 v[16];
; #pragma unroll
;         for (int i = 0; i < 16; ++i) v[i] = ok ? *(const f32x4*)(src + (size_t)(4 * i) * N) : (f32x4){0.f, 0.f, 0.f, 0.f};
.LBB0_198:
	s_mul_hi_i32 s6, s44, 0x2e8ba2e9
	s_lshr_b32 s7, s6, 31
	s_ashr_i32 s13, s6, 5
	s_add_i32 s13, s13, s7
	s_mul_i32 s6, s13, 0xffffd400
	s_add_i32 s14, s43, s6
	s_lshl_b32 s12, s13, 6
	v_add_u32_e32 v2, s14, v70
	v_cmp_gt_i32_e64 s[6:7], s22, v2
	v_or_b32_e32 v2, s12, v71
	v_mad_i64_i32 v[2:3], s[16:17], v2, s23, v[74:75]
	s_ashr_i32 s15, s14, 31
	v_lshl_add_u64 v[2:3], s[14:15], 2, v[2:3]
	v_lshl_add_u64 v[76:77], v[2:3], 0, v[68:69]
	v_mov_b32_e32 v6, 0
	v_mov_b32_e32 v2, 0
	v_mov_b32_e32 v3, 0
	v_mov_b32_e32 v4, 0
	v_mov_b32_e32 v5, 0
	s_and_saveexec_b64 s[16:17], s[6:7]
	s_cbranch_execz .LBB0_200
	global_load_dwordx4 v[2:5], v[76:77], off nt
.LBB0_200:
	s_or_b64 exec, exec, s[16:17]
	v_mov_b32_e32 v7, 0
	v_mov_b32_e32 v8, 0
	v_mov_b32_e32 v9, 0
	s_and_saveexec_b64 s[16:17], s[6:7]
	s_cbranch_execz .LBB0_202
	v_add_co_u32_e32 v6, vcc, 0x2c000, v76
	s_nop 1
	v_addc_co_u32_e32 v7, vcc, 0, v77, vcc
	global_load_dwordx4 v[6:9], v[6:7], off nt
.LBB0_202:
	s_or_b64 exec, exec, s[16:17]
	v_mov_b32_e32 v10, 0
	v_mov_b32_e32 v14, 0
	v_mov_b32_e32 v15, 0
	v_mov_b32_e32 v16, 0
	v_mov_b32_e32 v17, 0
	s_and_saveexec_b64 s[16:17], s[6:7]
	s_cbranch_execz .LBB0_204
	v_add_co_u32_e32 v12, vcc, 0x58000, v76
	s_nop 1
	v_addc_co_u32_e32 v13, vcc, 0, v77, vcc
	global_load_dwordx4 v[14:17], v[12:13], off nt
.LBB0_204:
	s_or_b64 exec, exec, s[16:17]
	v_mov_b32_e32 v11, 0
	v_mov_b32_e32 v12, 0
	v_mov_b32_e32 v13, 0
	s_and_saveexec_b64 s[16:17], s[6:7]
	s_cbranch_execz .LBB0_206
	v_add_co_u32_e32 v10, vcc, 0x84000, v76
	s_nop 1
	v_addc_co_u32_e32 v11, vcc, 0, v77, vcc
	global_load_dwordx4 v[10:13], v[10:11], off nt
.LBB0_206:
	s_or_b64 exec, exec, s[16:17]
	v_mov_b32_e32 v18, 0
	v_mov_b32_e32 v22, 0
	v_mov_b32_e32 v23, 0
	v_mov_b32_e32 v24, 0
	v_mov_b32_e32 v25, 0
	s_and_saveexec_b64 s[16:17], s[6:7]
	s_cbranch_execz .LBB0_208
	v_add_co_u32_e32 v20, vcc, 0xb0000, v76
	s_nop 1
	v_addc_co_u32_e32 v21, vcc, 0, v77, vcc
	global_load_dwordx4 v[22:25], v[20:21], off nt
.LBB0_208:
	s_or_b64 exec, exec, s[16:17]
	v_mov_b32_e32 v19, 0
	v_mov_b32_e32 v20, 0
	v_mov_b32_e32 v21, 0
	s_and_saveexec_b64 s[16:17], s[6:7]
	s_cbranch_execz .LBB0_210
	v_add_co_u32_e32 v18, vcc, 0xdc000, v76
	s_nop 1
	v_addc_co_u32_e32 v19, vcc, 0, v77, vcc
	global_load_dwordx4 v[18:21], v[18:19], off nt
.LBB0_210:
	s_or_b64 exec, exec, s[16:17]
	v_mov_b32_e32 v26, 0
	v_mov_b32_e32 v30, 0
	v_mov_b32_e32 v31, 0
	v_mov_b32_e32 v32, 0
	v_mov_b32_e32 v33, 0
	s_and_saveexec_b64 s[16:17], s[6:7]
	s_cbranch_execz .LBB0_212
	v_add_co_u32_e32 v28, vcc, 0x108000, v76
	s_nop 1
	v_addc_co_u32_e32 v29, vcc, 0, v77, vcc
	global_load_dwordx4 v[30:33], v[28:29], off nt
.LBB0_212:
	s_or_b64 exec, exec, s[16:17]
	v_mov_b32_e32 v27, 0
	v_mov_b32_e32 v28, 0
	v_mov_b32_e32 v29, 0
	s_and_saveexec_b64 s[16:17], s[6:7]
	s_cbranch_execz .LBB0_214
	v_add_co_u32_e32 v26, vcc, 0x134000, v76
	s_nop 1
	v_addc_co_u32_e32 v27, vcc, 0, v77, vcc
	global_load_dwordx4 v[26:29], v[26:27], off nt
.LBB0_214:
	s_or_b64 exec, exec, s[16:17]
	v_mov_b32_e32 v34, 0
	v_mov_b32_e32 v38, 0
	v_mov_b32_e32 v39, 0
	v_mov_b32_e32 v40, 0
	v_mov_b32_e32 v41, 0
	s_and_saveexec_b64 s[16:17], s[6:7]
	s_cbranch_execz .LBB0_216
	v_add_co_u32_e32 v36, vcc, 0x160000, v76
	s_nop 1
	v_addc_co_u32_e32 v37, vcc, 0, v77, vcc
	global_load_dwordx4 v[38:41], v[36:37], off nt
.LBB0_216:
	s_or_b64 exec, exec, s[16:17]
	v_mov_b32_e32 v35, 0
	v_mov_b32_e32 v36, 0
	v_mov_b32_e32 v37, 0
	s_and_saveexec_b64 s[16:17], s[6:7]
	s_cbranch_execz .LBB0_218
	v_add_co_u32_e32 v34, vcc, 0x18c000, v76
	s_nop 1
	v_addc_co_u32_e32 v35, vcc, 0, v77, vcc
	global_load_dwordx4 v[34:37], v[34:35], off nt
.LBB0_218:
	s_or_b64 exec, exec, s[16:17]
	v_mov_b32_e32 v42, 0
	v_mov_b32_e32 v46, 0
	v_mov_b32_e32 v47, 0
	v_mov_b32_e32 v48, 0
	v_mov_b32_e32 v49, 0
	s_and_saveexec_b64 s[16:17], s[6:7]
	s_cbranch_execz .LBB0_220
	v_add_co_u32_e32 v44, vcc, 0x1b8000, v76
	s_nop 1
	v_addc_co_u32_e32 v45, vcc, 0, v77, vcc
	global_load_dwordx4 v[46:49], v[44:45], off nt
.LBB0_220:
	s_or_b64 exec, exec, s[16:17]
	v_mov_b32_e32 v43, 0
	v_mov_b32_e32 v44, 0
	v_mov_b32_e32 v45, 0
	s_and_saveexec_b64 s[16:17], s[6:7]
	s_cbranch_execz .LBB0_222
	v_add_co_u32_e32 v42, vcc, 0x1e4000, v76
	s_nop 1
	v_addc_co_u32_e32 v43, vcc, 0, v77, vcc
	global_load_dwordx4 v[42:45], v[42:43], off nt
.LBB0_222:
	s_or_b64 exec, exec, s[16:17]
	v_mov_b32_e32 v50, 0
	v_mov_b32_e32 v54, 0
	v_mov_b32_e32 v55, 0
	v_mov_b32_e32 v56, 0
	v_mov_b32_e32 v57, 0
	s_and_saveexec_b64 s[16:17], s[6:7]
	s_cbranch_execz .LBB0_224
	v_add_co_u32_e32 v52, vcc, 0x210000, v76
	s_nop 1
	v_addc_co_u32_e32 v53, vcc, 0, v77, vcc
	global_load_dwordx4 v[54:57], v[52:53], off nt
.LBB0_224:
	s_or_b64 exec, exec, s[16:17]
	v_mov_b32_e32 v51, 0
	v_mov_b32_e32 v52, 0
	v_mov_b32_e32 v53, 0
	s_and_saveexec_b64 s[16:17], s[6:7]
	s_cbranch_execz .LBB0_226
	v_add_co_u32_e32 v50, vcc, 0x23c000, v76
	s_nop 1
	v_addc_co_u32_e32 v51, vcc, 0, v77, vcc
	global_load_dwordx4 v[50:53], v[50:51], off nt
.LBB0_226:
	s_or_b64 exec, exec, s[16:17]
	v_mov_b32_e32 v58, 0
	v_mov_b32_e32 v62, 0
	v_mov_b32_e32 v63, 0
	v_mov_b32_e32 v64, 0
	v_mov_b32_e32 v65, 0
	s_and_saveexec_b64 s[16:17], s[6:7]
	s_cbranch_execz .LBB0_228
	v_add_co_u32_e32 v60, vcc, 0x268000, v76
	s_nop 1
	v_addc_co_u32_e32 v61, vcc, 0, v77, vcc
	global_load_dwordx4 v[62:65], v[60:61], off nt
.LBB0_228:
	s_or_b64 exec, exec, s[16:17]
	v_mov_b32_e32 v59, 0
	v_mov_b32_e32 v60, 0
	v_mov_b32_e32 v61, 0
	s_and_saveexec_b64 s[16:17], s[6:7]
	s_cbranch_execz .LBB0_230
	v_add_co_u32_e32 v58, vcc, 0x294000, v76
	s_nop 1
	v_addc_co_u32_e32 v59, vcc, 0, v77, vcc
	global_load_dwordx4 v[58:61], v[58:59], off nt
